# E35 EpiIn q/k gain branch: second gain-vector pair kept resident in dead fragment registers instead of 8 reload+stall round trips per unit (on top of E34)
# baseline (speedup 1.0000x reference)
;     __device__ __forceinline__ void operator()(const Acc& acc, const Unit& u, int wr, int wc, int fr, int fq) const {
;     ...
;             if (pn < 4) {
;                 const float* g = (pn < 2) ? qg : kg; bf16_t* dst = (pn < 2) ? Q : Kb;
;                 const float post = (pn < 2) ? 0.125f * LOG2E : 1.0f;
;                 const int head = 4 * (pn & 1) + wc;
; #pragma unroll
;                 for (int ai = 0; ai < 2; ++ai)
; #pragma unroll
;                     for (int m = 0; m < 4; ++m) {
;                         const int row = u.pm * 256 + ai * 128 + wr * 64 + m * 16 + fr;
;                         const float rs = rsv[ai][m];
;                         f32x4 v[2][2]; float ss = 0.f;
; #pragma unroll
;                         for (int bj = 0; bj < 2; ++bj)
; #pragma unroll
;                             for (int n = 0; n < 2; ++n) { v[bj][n] = acc[ai][bj][m][n] * rs; const f32x4 x = v[bj][n]; ss += (x[0] * x[0] + x[1] * x[1]) + (x[2] * x[2] + x[3] * x[3]); }
;                         ss += xshfl<16>(ss); ss += xshfl<32>(ss);
;                         const float hn = __builtin_amdgcn_rsqf(ss * (1.f / 64.f) + EPS) * post;
; #pragma unroll
;                         for (int bj = 0; bj < 2; ++bj) {
;                             float o[8];
; #pragma unroll
;                             for (int n = 0; n < 2; ++n) { const f32x4 gv = *(const f32x4*)(g + 32 * bj + 8 * fq + 4 * n);
; #pragma unroll
;                                 for (int j = 0; j < 4; ++j) o[4 * n + j] = v[bj][n][j] * hn * gv[j]; }
;                             st16(dst + (size_t)row * 512 + head * 64 + 32 * bj + 8 * fq, o);
;                         }
;                         asm volatile("" ::: "memory");
;                     }
.LBB0_207:
	s_andn2_b64 vcc, exec, s[0:1]
	s_cbranch_vccnz .LBB0_209
	s_cmp_lt_i32 s60, 2
	s_cselect_b64 vcc, -1, 0
	s_and_b64 s[0:1], vcc, exec
	s_mov_b32 s0, 0x6000000
	s_cselect_b32 s34, s0, 0x7000000
	s_cselect_b32 s0, s43, s47
	s_cselect_b32 s1, s42, s46
	s_add_u32 s0, s0, s18
	s_addc_u32 s1, s1, s19
	v_lshlrev_b32_e32 v171, 2, v136
	global_load_dwordx4 v[186:189], v171, s[0:1]
	global_load_dwordx4 v[190:193], v171, s[0:1] offset:16
	global_load_dwordx4 v[216:219], v171, s[0:1] offset:128
	global_load_dwordx4 v[220:223], v171, s[0:1] offset:144
	v_pk_mul_f32 v[122:123], v[184:185], v[122:123] op_sel_hi:[0,1]
	v_pk_mul_f32 v[120:121], v[184:185], v[120:121] op_sel_hi:[0,1]
	v_pk_mul_f32 v[126:127], v[184:185], v[126:127] op_sel_hi:[0,1]
	v_pk_mul_f32 v[124:125], v[184:185], v[124:125] op_sel_hi:[0,1]
	v_pk_mul_f32 v[194:195], v[184:185], v[118:119] op_sel_hi:[0,1]
	v_pk_mul_f32 v[196:197], v[184:185], v[116:117] op_sel_hi:[0,1]
	v_pk_mul_f32 v[198:199], v[184:185], v[114:115] op_sel_hi:[0,1]
	v_pk_mul_f32 v[184:185], v[184:185], v[112:113] op_sel_hi:[0,1]
	v_add_u32_e32 v112, s23, v139
	v_pk_mul_f32 v[114:115], v[122:123], v[122:123]
	v_pk_mul_f32 v[116:117], v[120:121], v[120:121]
	v_pk_mul_f32 v[118:119], v[126:127], v[126:127]
	v_pk_mul_f32 v[200:201], v[124:125], v[124:125]
	v_mul_f32_e32 v202, v196, v196
	v_mul_f32_e32 v204, v194, v194
	v_ashrrev_i32_e32 v113, 31, v112
	v_pk_mov_b32 v[206:207], v[116:117], v[114:115] op_sel:[1,0]
	v_mov_b32_e32 v117, v115
	v_pk_mov_b32 v[114:115], v[200:201], v[118:119] op_sel:[1,0]
	v_mov_b32_e32 v201, v119
	v_pk_fma_f32 v[118:119], v[196:197], v[196:197], v[202:203] op_sel_hi:[1,1,0]
	v_pk_fma_f32 v[202:203], v[194:195], v[194:195], v[204:205] op_sel_hi:[1,1,0]
	v_lshlrev_b64 v[204:205], 10, v[112:113]
	v_pk_add_f32 v[112:113], v[206:207], v[116:117]
	v_pk_add_f32 v[114:115], v[114:115], v[200:201]
	v_pk_add_f32 v[112:113], v[112:113], v[112:113] op_sel_hi:[0,1]
	v_pk_add_f32 v[114:115], v[114:115], v[114:115] op_sel_hi:[0,1]
	v_mul_f32_e32 v118, v184, v184
	v_mul_f32_e32 v202, v185, v185
	v_mul_f32_e32 v112, v198, v198
	v_mul_f32_e32 v114, v199, v199
	v_pk_add_f32 v[116:117], v[118:119], v[202:203]
	v_pk_add_f32 v[112:113], v[112:113], v[114:115]
	v_mov_b32_e32 v156, 0x3e38aa3b
	v_pk_add_f32 v[112:113], v[116:117], v[112:113]
	v_cndmask_b32_e32 v173, 1.0, v156, vcc
	v_add_f32_e32 v112, v112, v113
	ds_swizzle_b32 v113, v112 offset:swizzle(SWAP,16)
	v_cmp_eq_u32_e32 vcc, 0, v214
	s_add_u32 s30, s30, s34
	s_addc_u32 s31, s31, 0
	s_lshl_b32 s34, s60, 2
	s_waitcnt lgkmcnt(0)
	v_add_f32_e32 v112, v112, v113
	v_mov_b32_e32 v113, v112
	v_mov_b32_e32 v114, v112
	s_nop 1
	v_permlane32_swap_b32_e32 v113, v114
	v_cndmask_b32_e32 v113, v113, v114, vcc
	v_add_f32_e32 v112, v112, v113
	s_and_b32 s34, s34, 4
	v_fmamk_f32 v112, v112, 0x3c800000, v212
	s_or_b32 s34, s34, s88
	v_rsq_f32_e32 v114, v112
	s_lshl_b32 s34, s34, 7
	s_add_u32 s30, s30, s34
	v_lshlrev_b32_e32 v156, 1, v136
	s_addc_u32 s31, s31, 0
	v_lshl_add_u64 v[112:113], s[30:31], 0, v[156:157]
	v_mul_f32_e32 v156, v173, v114
	v_pk_mul_f32 v[114:115], v[120:121], v[156:157] op_sel_hi:[1,0]
	v_pk_mul_f32 v[116:117], v[122:123], v[156:157] op_sel_hi:[1,0]
	v_pk_mul_f32 v[118:119], v[124:125], v[156:157] op_sel_hi:[1,0]
	v_pk_mul_f32 v[120:121], v[126:127], v[156:157] op_sel_hi:[1,0]
	v_lshl_add_u64 v[200:201], v[112:113], 0, v[204:205]
	v_pk_mul_f32 v[122:123], v[196:197], v[156:157] op_sel_hi:[1,0]
	v_pk_mul_f32 v[124:125], v[194:195], v[156:157] op_sel_hi:[1,0]
	v_pk_mul_f32 v[126:127], v[184:185], v[156:157] op_sel_hi:[1,0]
	v_pk_mul_f32 v[184:185], v[198:199], v[156:157] op_sel_hi:[1,0]
	v_pk_mul_f32 v[110:111], v[182:183], v[110:111] op_sel_hi:[0,1]
	v_pk_mul_f32 v[108:109], v[182:183], v[108:109] op_sel_hi:[0,1]
	v_pk_mul_f32 v[106:107], v[182:183], v[106:107] op_sel_hi:[0,1]
	v_pk_mul_f32 v[104:105], v[182:183], v[104:105] op_sel_hi:[0,1]
	v_pk_mul_f32 v[94:95], v[180:181], v[94:95] op_sel_hi:[0,1]
	v_pk_mul_f32 v[92:93], v[180:181], v[92:93] op_sel_hi:[0,1]
	v_pk_mul_f32 v[90:91], v[180:181], v[90:91] op_sel_hi:[0,1]
	v_pk_mul_f32 v[88:89], v[180:181], v[88:89] op_sel_hi:[0,1]
	v_pk_mul_f32 v[78:79], v[178:179], v[78:79] op_sel_hi:[0,1]
	v_pk_mul_f32 v[76:77], v[178:179], v[76:77] op_sel_hi:[0,1]
	s_waitcnt vmcnt(1)
	v_pk_mul_f32 v[114:115], v[186:187], v[114:115]
	v_pk_mul_f32 v[116:117], v[188:189], v[116:117]
	s_waitcnt vmcnt(0)
;     __device__ __forceinline__ void operator()(const Acc& acc, const Unit& u, int wr, int wc, int fr, int fq) const {
;     ...
;             if (pn < 4) {
;                 const float* g = (pn < 2) ? qg : kg; bf16_t* dst = (pn < 2) ? Q : Kb;
;                 const float post = (pn < 2) ? 0.125f * LOG2E : 1.0f;
;                 const int head = 4 * (pn & 1) + wc;
; #pragma unroll
;                 for (int ai = 0; ai < 2; ++ai)
; #pragma unroll
;                     for (int m = 0; m < 4; ++m) {
;                         const int row = u.pm * 256 + ai * 128 + wr * 64 + m * 16 + fr;
;                         const float rs = rsv[ai][m];
;                         f32x4 v[2][2]; float ss = 0.f;
; #pragma unroll
;                         for (int bj = 0; bj < 2; ++bj)
; #pragma unroll
;                             for (int n = 0; n < 2; ++n) { v[bj][n] = acc[ai][bj][m][n] * rs; const f32x4 x = v[bj][n]; ss += (x[0] * x[0] + x[1] * x[1]) + (x[2] * x[2] + x[3] * x[3]); }
;                         ss += xshfl<16>(ss); ss += xshfl<32>(ss);
;                         const float hn = __builtin_amdgcn_rsqf(ss * (1.f / 64.f) + EPS) * post;
; #pragma unroll
;                         for (int bj = 0; bj < 2; ++bj) {
;                             float o[8];
; #pragma unroll
;                             for (int n = 0; n < 2; ++n) { const f32x4 gv = *(const f32x4*)(g + 32 * bj + 8 * fq + 4 * n);
; #pragma unroll
;                                 for (int j = 0; j < 4; ++j) o[4 * n + j] = v[bj][n][j] * hn * gv[j]; }
;                             st16(dst + (size_t)row * 512 + head * 64 + 32 * bj + 8 * fq, o);
;                         }
;                         asm volatile("" ::: "memory");
;                     }
	v_pk_mul_f32 v[118:119], v[190:191], v[118:119]
	v_pk_mul_f32 v[120:121], v[192:193], v[120:121]
	v_cvt_pk_bf16_f32 v114, v114, v115
	v_cvt_pk_bf16_f32 v115, v116, v117
	v_cvt_pk_bf16_f32 v116, v118, v119
	v_cvt_pk_bf16_f32 v117, v120, v121
	global_store_dwordx4 v[200:201], v[114:117], off
	s_nop 1
	v_pk_mul_f32 v[74:75], v[178:179], v[74:75] op_sel_hi:[0,1]
	v_pk_mul_f32 v[72:73], v[178:179], v[72:73] op_sel_hi:[0,1]
	v_pk_mul_f32 v[62:63], v[176:177], v[62:63] op_sel_hi:[0,1]
	v_pk_mul_f32 v[60:61], v[176:177], v[60:61] op_sel_hi:[0,1]
	v_pk_mul_f32 v[58:59], v[176:177], v[58:59] op_sel_hi:[0,1]
	v_pk_mul_f32 v[56:57], v[176:177], v[56:57] op_sel_hi:[0,1]
	v_pk_mul_f32 v[46:47], v[174:175], v[46:47] op_sel_hi:[0,1]
	v_pk_mul_f32 v[44:45], v[174:175], v[44:45] op_sel_hi:[0,1]
	v_pk_mul_f32 v[42:43], v[174:175], v[42:43] op_sel_hi:[0,1]
	v_pk_mul_f32 v[40:41], v[174:175], v[40:41] op_sel_hi:[0,1]
	v_pk_mul_f32 v[30:31], v[172:173], v[30:31] op_sel_hi:[0,1]
	v_pk_mul_f32 v[28:29], v[172:173], v[28:29] op_sel_hi:[0,1]
	v_pk_mul_f32 v[26:27], v[172:173], v[26:27] op_sel_hi:[0,1]
	v_pk_mul_f32 v[24:25], v[172:173], v[24:25] op_sel_hi:[0,1]
	v_pk_mul_f32 v[14:15], v[170:171], v[14:15] op_sel_hi:[0,1]
	v_pk_mul_f32 v[12:13], v[170:171], v[12:13] op_sel_hi:[0,1]
	v_pk_mul_f32 v[10:11], v[170:171], v[10:11] op_sel_hi:[0,1]
	v_pk_mul_f32 v[8:9], v[170:171], v[8:9] op_sel_hi:[0,1]
	v_pk_mul_f32 v[114:115], v[216:217], v[122:123]
	v_pk_mul_f32 v[116:117], v[218:219], v[124:125]
	v_pk_mul_f32 v[118:119], v[220:221], v[126:127]
	v_pk_mul_f32 v[120:121], v[222:223], v[184:185]
	v_cvt_pk_bf16_f32 v114, v114, v115
	v_cvt_pk_bf16_f32 v115, v116, v117
	v_cvt_pk_bf16_f32 v116, v118, v119
	v_cvt_pk_bf16_f32 v117, v120, v121
	global_store_dwordx4 v[200:201], v[114:117], off offset:64
	global_load_dwordx4 v[114:117], v171, s[0:1]
	global_load_dwordx4 v[118:121], v171, s[0:1] offset:16
	v_pk_mul_f32 v[122:123], v[182:183], v[102:103] op_sel_hi:[0,1]
	v_pk_mul_f32 v[124:125], v[182:183], v[100:101] op_sel_hi:[0,1]
	v_pk_mul_f32 v[126:127], v[182:183], v[98:99] op_sel_hi:[0,1]
	v_pk_mul_f32 v[182:183], v[182:183], v[96:97] op_sel_hi:[0,1]
	v_pk_mul_f32 v[96:97], v[110:111], v[110:111]
	v_pk_mul_f32 v[98:99], v[108:109], v[108:109]
	v_pk_mul_f32 v[100:101], v[106:107], v[106:107]
	v_pk_mul_f32 v[102:103], v[104:105], v[104:105]
	v_pk_mov_b32 v[186:187], v[98:99], v[96:97] op_sel:[1,0]
	v_mov_b32_e32 v99, v97
	v_pk_mov_b32 v[96:97], v[102:103], v[100:101] op_sel:[1,0]
	v_mov_b32_e32 v103, v101
	v_mul_f32_e32 v156, v124, v124
	v_mul_f32_e32 v184, v122, v122
	v_pk_add_f32 v[98:99], v[186:187], v[98:99]
	v_pk_add_f32 v[96:97], v[96:97], v[102:103]
	v_pk_fma_f32 v[100:101], v[124:125], v[124:125], v[156:157] op_sel_hi:[1,1,0]
	v_pk_fma_f32 v[184:185], v[122:123], v[122:123], v[184:185] op_sel_hi:[1,1,0]
	v_pk_add_f32 v[98:99], v[98:99], v[98:99] op_sel_hi:[0,1]
	v_pk_add_f32 v[96:97], v[96:97], v[96:97] op_sel_hi:[0,1]
	v_mul_f32_e32 v100, v182, v182
	v_mul_f32_e32 v184, v183, v183
	v_mul_f32_e32 v98, v126, v126
	v_mul_f32_e32 v96, v127, v127
	v_pk_add_f32 v[100:101], v[100:101], v[184:185]
	v_pk_add_f32 v[96:97], v[98:99], v[96:97]
	s_nop 0
	v_pk_add_f32 v[96:97], v[100:101], v[96:97]
	s_nop 0
	v_add_f32_e32 v97, v96, v97
	ds_swizzle_b32 v98, v97 offset:swizzle(SWAP,16)
	v_add_u32_e32 v96, s23, v143
	s_waitcnt lgkmcnt(0)
	v_add_f32_e32 v97, v97, v98
	v_mov_b32_e32 v98, v97
	v_mov_b32_e32 v99, v97
	s_nop 1
	v_permlane32_swap_b32_e32 v98, v99
	v_cndmask_b32_e32 v98, v98, v99, vcc
	v_add_f32_e32 v97, v97, v98
	v_fmamk_f32 v97, v97, 0x3c800000, v212
	v_rsq_f32_e32 v98, v97
	v_ashrrev_i32_e32 v97, 31, v96
	v_lshlrev_b64 v[96:97], 10, v[96:97]
	v_lshl_add_u64 v[184:185], v[112:113], 0, v[96:97]
	v_mul_f32_e32 v156, v173, v98
	v_pk_mul_f32 v[96:97], v[108:109], v[156:157] op_sel_hi:[1,0]
	v_pk_mul_f32 v[98:99], v[110:111], v[156:157] op_sel_hi:[1,0]
	v_pk_mul_f32 v[100:101], v[104:105], v[156:157] op_sel_hi:[1,0]
	v_pk_mul_f32 v[102:103], v[106:107], v[156:157] op_sel_hi:[1,0]
	v_pk_mul_f32 v[104:105], v[124:125], v[156:157] op_sel_hi:[1,0]
	v_pk_mul_f32 v[106:107], v[122:123], v[156:157] op_sel_hi:[1,0]
	v_pk_mul_f32 v[108:109], v[182:183], v[156:157] op_sel_hi:[1,0]
	v_pk_mul_f32 v[110:111], v[126:127], v[156:157] op_sel_hi:[1,0]
	s_waitcnt vmcnt(1)
	v_pk_mul_f32 v[96:97], v[114:115], v[96:97]
	v_pk_mul_f32 v[98:99], v[116:117], v[98:99]
	s_waitcnt vmcnt(0)
	v_pk_mul_f32 v[100:101], v[118:119], v[100:101]
	v_pk_mul_f32 v[102:103], v[120:121], v[102:103]
	v_cvt_pk_bf16_f32 v96, v96, v97
	v_cvt_pk_bf16_f32 v97, v98, v99
	v_cvt_pk_bf16_f32 v98, v100, v101
	v_cvt_pk_bf16_f32 v99, v102, v103
	global_store_dwordx4 v[184:185], v[96:99], off
	s_nop 1
	v_pk_mul_f32 v[96:97], v[216:217], v[104:105]
	v_pk_mul_f32 v[98:99], v[218:219], v[106:107]
	v_pk_mul_f32 v[100:101], v[220:221], v[108:109]
	v_pk_mul_f32 v[102:103], v[222:223], v[110:111]
	v_cvt_pk_bf16_f32 v96, v96, v97
	v_cvt_pk_bf16_f32 v97, v98, v99
	v_cvt_pk_bf16_f32 v98, v100, v101
	v_cvt_pk_bf16_f32 v99, v102, v103
	global_store_dwordx4 v[184:185], v[96:99], off offset:64
	global_load_dwordx4 v[96:99], v171, s[0:1]
	global_load_dwordx4 v[100:103], v171, s[0:1] offset:16
	v_pk_mul_f32 v[104:105], v[180:181], v[86:87] op_sel_hi:[0,1]
	v_pk_mul_f32 v[106:107], v[180:181], v[84:85] op_sel_hi:[0,1]
	v_pk_mul_f32 v[108:109], v[180:181], v[82:83] op_sel_hi:[0,1]
	v_pk_mul_f32 v[110:111], v[180:181], v[80:81] op_sel_hi:[0,1]
	v_pk_mul_f32 v[80:81], v[94:95], v[94:95]
	v_pk_mul_f32 v[82:83], v[92:93], v[92:93]
	v_pk_mul_f32 v[84:85], v[90:91], v[90:91]
	v_pk_mul_f32 v[86:87], v[88:89], v[88:89]
	v_pk_mov_b32 v[118:119], v[82:83], v[80:81] op_sel:[1,0]
	v_mov_b32_e32 v83, v81
	v_pk_mov_b32 v[80:81], v[86:87], v[84:85] op_sel:[1,0]
	v_mov_b32_e32 v87, v85
	v_mul_f32_e32 v114, v106, v106
	v_mul_f32_e32 v116, v104, v104
	v_pk_add_f32 v[82:83], v[118:119], v[82:83]
	v_pk_add_f32 v[80:81], v[80:81], v[86:87]
	v_pk_fma_f32 v[84:85], v[106:107], v[106:107], v[114:115] op_sel_hi:[1,1,0]
	v_pk_fma_f32 v[114:115], v[104:105], v[104:105], v[116:117] op_sel_hi:[1,1,0]
	v_pk_add_f32 v[82:83], v[82:83], v[82:83] op_sel_hi:[0,1]
	v_pk_add_f32 v[80:81], v[80:81], v[80:81] op_sel_hi:[0,1]
	v_mul_f32_e32 v84, v110, v110
	v_mul_f32_e32 v114, v111, v111
	v_mul_f32_e32 v82, v108, v108
	v_mul_f32_e32 v80, v109, v109
	v_pk_add_f32 v[84:85], v[84:85], v[114:115]
	v_pk_add_f32 v[80:81], v[82:83], v[80:81]
	s_nop 0
	v_pk_add_f32 v[80:81], v[84:85], v[80:81]
	s_nop 0
	v_add_f32_e32 v81, v80, v81
	ds_swizzle_b32 v82, v81 offset:swizzle(SWAP,16)
	v_add_u32_e32 v80, s23, v145
	s_waitcnt lgkmcnt(0)
;     __device__ __forceinline__ void operator()(const Acc& acc, const Unit& u, int wr, int wc, int fr, int fq) const {
;     ...
;             if (pn < 4) {
;                 const float* g = (pn < 2) ? qg : kg; bf16_t* dst = (pn < 2) ? Q : Kb;
;                 const float post = (pn < 2) ? 0.125f * LOG2E : 1.0f;
;                 const int head = 4 * (pn & 1) + wc;
; #pragma unroll
;                 for (int ai = 0; ai < 2; ++ai)
; #pragma unroll
;                     for (int m = 0; m < 4; ++m) {
;                         const int row = u.pm * 256 + ai * 128 + wr * 64 + m * 16 + fr;
;                         const float rs = rsv[ai][m];
;                         f32x4 v[2][2]; float ss = 0.f;
; #pragma unroll
;                         for (int bj = 0; bj < 2; ++bj)
; #pragma unroll
;                             for (int n = 0; n < 2; ++n) { v[bj][n] = acc[ai][bj][m][n] * rs; const f32x4 x = v[bj][n]; ss += (x[0] * x[0] + x[1] * x[1]) + (x[2] * x[2] + x[3] * x[3]); }
;                         ss += xshfl<16>(ss); ss += xshfl<32>(ss);
;                         const float hn = __builtin_amdgcn_rsqf(ss * (1.f / 64.f) + EPS) * post;
; #pragma unroll
;                         for (int bj = 0; bj < 2; ++bj) {
;                             float o[8];
; #pragma unroll
;                             for (int n = 0; n < 2; ++n) { const f32x4 gv = *(const f32x4*)(g + 32 * bj + 8 * fq + 4 * n);
; #pragma unroll
;                                 for (int j = 0; j < 4; ++j) o[4 * n + j] = v[bj][n][j] * hn * gv[j]; }
;                             st16(dst + (size_t)row * 512 + head * 64 + 32 * bj + 8 * fq, o);
;                         }
;                         asm volatile("" ::: "memory");
;                     }
	v_add_f32_e32 v81, v81, v82
	v_mov_b32_e32 v82, v81
	v_mov_b32_e32 v83, v81
	s_nop 1
	v_permlane32_swap_b32_e32 v82, v83
	v_cndmask_b32_e32 v82, v82, v83, vcc
	v_add_f32_e32 v81, v81, v82
	v_fmamk_f32 v81, v81, 0x3c800000, v212
	v_rsq_f32_e32 v82, v81
	v_ashrrev_i32_e32 v81, 31, v80
	v_lshlrev_b64 v[80:81], 10, v[80:81]
	v_lshl_add_u64 v[114:115], v[112:113], 0, v[80:81]
	v_mul_f32_e32 v116, v173, v82
	v_pk_mul_f32 v[80:81], v[92:93], v[116:117] op_sel_hi:[1,0]
	v_pk_mul_f32 v[82:83], v[94:95], v[116:117] op_sel_hi:[1,0]
	v_pk_mul_f32 v[84:85], v[88:89], v[116:117] op_sel_hi:[1,0]
	v_pk_mul_f32 v[86:87], v[90:91], v[116:117] op_sel_hi:[1,0]
	v_pk_mul_f32 v[88:89], v[106:107], v[116:117] op_sel_hi:[1,0]
	v_pk_mul_f32 v[90:91], v[104:105], v[116:117] op_sel_hi:[1,0]
	v_pk_mul_f32 v[92:93], v[110:111], v[116:117] op_sel_hi:[1,0]
	v_pk_mul_f32 v[94:95], v[108:109], v[116:117] op_sel_hi:[1,0]
	s_waitcnt vmcnt(1)
	v_pk_mul_f32 v[80:81], v[96:97], v[80:81]
	v_pk_mul_f32 v[82:83], v[98:99], v[82:83]
	s_waitcnt vmcnt(0)
	v_pk_mul_f32 v[84:85], v[100:101], v[84:85]
	v_pk_mul_f32 v[86:87], v[102:103], v[86:87]
	v_cvt_pk_bf16_f32 v80, v80, v81
	v_cvt_pk_bf16_f32 v81, v82, v83
	v_cvt_pk_bf16_f32 v82, v84, v85
	v_cvt_pk_bf16_f32 v83, v86, v87
	global_store_dwordx4 v[114:115], v[80:83], off
	s_nop 1
	v_pk_mul_f32 v[80:81], v[216:217], v[88:89]
	v_pk_mul_f32 v[82:83], v[218:219], v[90:91]
	v_pk_mul_f32 v[84:85], v[220:221], v[92:93]
	v_pk_mul_f32 v[86:87], v[222:223], v[94:95]
	v_cvt_pk_bf16_f32 v80, v80, v81
	v_cvt_pk_bf16_f32 v81, v82, v83
	v_cvt_pk_bf16_f32 v82, v84, v85
	v_cvt_pk_bf16_f32 v83, v86, v87
	global_store_dwordx4 v[114:115], v[80:83], off offset:64
	global_load_dwordx4 v[80:83], v171, s[0:1]
	global_load_dwordx4 v[84:87], v171, s[0:1] offset:16
	v_pk_mul_f32 v[88:89], v[178:179], v[70:71] op_sel_hi:[0,1]
	v_pk_mul_f32 v[90:91], v[178:179], v[68:69] op_sel_hi:[0,1]
	v_pk_mul_f32 v[92:93], v[178:179], v[66:67] op_sel_hi:[0,1]
	v_pk_mul_f32 v[94:95], v[178:179], v[64:65] op_sel_hi:[0,1]
	v_pk_mul_f32 v[64:65], v[78:79], v[78:79]
	v_pk_mul_f32 v[66:67], v[76:77], v[76:77]
	v_pk_mul_f32 v[68:69], v[74:75], v[74:75]
	v_pk_mul_f32 v[70:71], v[72:73], v[72:73]
	v_pk_mov_b32 v[100:101], v[66:67], v[64:65] op_sel:[1,0]
	v_mov_b32_e32 v67, v65
	v_pk_mov_b32 v[64:65], v[70:71], v[68:69] op_sel:[1,0]
	v_mov_b32_e32 v71, v69
	v_mul_f32_e32 v96, v90, v90
	v_mul_f32_e32 v98, v88, v88
	v_pk_add_f32 v[66:67], v[100:101], v[66:67]
	v_pk_add_f32 v[64:65], v[64:65], v[70:71]
	v_pk_fma_f32 v[68:69], v[90:91], v[90:91], v[96:97] op_sel_hi:[1,1,0]
	v_pk_fma_f32 v[96:97], v[88:89], v[88:89], v[98:99] op_sel_hi:[1,1,0]
	v_pk_add_f32 v[66:67], v[66:67], v[66:67] op_sel_hi:[0,1]
	v_pk_add_f32 v[64:65], v[64:65], v[64:65] op_sel_hi:[0,1]
	v_mul_f32_e32 v68, v94, v94
	v_mul_f32_e32 v96, v95, v95
	v_mul_f32_e32 v66, v92, v92
	v_mul_f32_e32 v64, v93, v93
	v_pk_add_f32 v[68:69], v[68:69], v[96:97]
	v_pk_add_f32 v[64:65], v[66:67], v[64:65]
	s_nop 0
	v_pk_add_f32 v[64:65], v[68:69], v[64:65]
	s_nop 0
	v_add_f32_e32 v65, v64, v65
	ds_swizzle_b32 v66, v65 offset:swizzle(SWAP,16)
	v_add_u32_e32 v64, s23, v147
	s_waitcnt lgkmcnt(0)
	v_add_f32_e32 v65, v65, v66
	v_mov_b32_e32 v66, v65
	v_mov_b32_e32 v67, v65
	s_nop 1
	v_permlane32_swap_b32_e32 v66, v67
	v_cndmask_b32_e32 v66, v66, v67, vcc
	v_add_f32_e32 v65, v65, v66
	v_fmamk_f32 v65, v65, 0x3c800000, v212
	v_rsq_f32_e32 v66, v65
	v_ashrrev_i32_e32 v65, 31, v64
	v_lshlrev_b64 v[64:65], 10, v[64:65]
	v_lshl_add_u64 v[96:97], v[112:113], 0, v[64:65]
	v_mul_f32_e32 v98, v173, v66
	v_pk_mul_f32 v[64:65], v[76:77], v[98:99] op_sel_hi:[1,0]
	v_pk_mul_f32 v[66:67], v[78:79], v[98:99] op_sel_hi:[1,0]
	v_pk_mul_f32 v[68:69], v[72:73], v[98:99] op_sel_hi:[1,0]
	v_pk_mul_f32 v[70:71], v[74:75], v[98:99] op_sel_hi:[1,0]
	v_pk_mul_f32 v[72:73], v[90:91], v[98:99] op_sel_hi:[1,0]
	v_pk_mul_f32 v[74:75], v[88:89], v[98:99] op_sel_hi:[1,0]
	v_pk_mul_f32 v[76:77], v[94:95], v[98:99] op_sel_hi:[1,0]
	v_pk_mul_f32 v[78:79], v[92:93], v[98:99] op_sel_hi:[1,0]
	s_waitcnt vmcnt(1)
	v_pk_mul_f32 v[64:65], v[80:81], v[64:65]
	v_pk_mul_f32 v[66:67], v[82:83], v[66:67]
	s_waitcnt vmcnt(0)
	v_pk_mul_f32 v[68:69], v[84:85], v[68:69]
	v_pk_mul_f32 v[70:71], v[86:87], v[70:71]
	v_cvt_pk_bf16_f32 v64, v64, v65
	v_cvt_pk_bf16_f32 v65, v66, v67
	v_cvt_pk_bf16_f32 v66, v68, v69
	v_cvt_pk_bf16_f32 v67, v70, v71
	global_store_dwordx4 v[96:97], v[64:67], off
	s_nop 1
	v_pk_mul_f32 v[64:65], v[216:217], v[72:73]
	v_pk_mul_f32 v[66:67], v[218:219], v[74:75]
	v_pk_mul_f32 v[68:69], v[220:221], v[76:77]
	v_pk_mul_f32 v[70:71], v[222:223], v[78:79]
	v_cvt_pk_bf16_f32 v64, v64, v65
	v_cvt_pk_bf16_f32 v65, v66, v67
	v_cvt_pk_bf16_f32 v66, v68, v69
	v_cvt_pk_bf16_f32 v67, v70, v71
	global_store_dwordx4 v[96:97], v[64:67], off offset:64
	global_load_dwordx4 v[64:67], v171, s[0:1]
	global_load_dwordx4 v[68:71], v171, s[0:1] offset:16
	v_pk_mul_f32 v[72:73], v[176:177], v[54:55] op_sel_hi:[0,1]
	v_pk_mul_f32 v[74:75], v[176:177], v[52:53] op_sel_hi:[0,1]
	v_pk_mul_f32 v[76:77], v[176:177], v[50:51] op_sel_hi:[0,1]
	v_pk_mul_f32 v[78:79], v[176:177], v[48:49] op_sel_hi:[0,1]
	v_pk_mul_f32 v[48:49], v[62:63], v[62:63]
	v_pk_mul_f32 v[50:51], v[60:61], v[60:61]
	v_pk_mul_f32 v[52:53], v[58:59], v[58:59]
	v_pk_mul_f32 v[54:55], v[56:57], v[56:57]
	v_pk_mov_b32 v[84:85], v[50:51], v[48:49] op_sel:[1,0]
	v_mov_b32_e32 v51, v49
	v_pk_mov_b32 v[48:49], v[54:55], v[52:53] op_sel:[1,0]
	v_mov_b32_e32 v55, v53
	v_mul_f32_e32 v80, v74, v74
	v_mul_f32_e32 v82, v72, v72
	v_pk_add_f32 v[50:51], v[84:85], v[50:51]
	v_pk_add_f32 v[48:49], v[48:49], v[54:55]
	v_pk_fma_f32 v[52:53], v[74:75], v[74:75], v[80:81] op_sel_hi:[1,1,0]
	v_pk_fma_f32 v[80:81], v[72:73], v[72:73], v[82:83] op_sel_hi:[1,1,0]
	v_pk_add_f32 v[50:51], v[50:51], v[50:51] op_sel_hi:[0,1]
	v_pk_add_f32 v[48:49], v[48:49], v[48:49] op_sel_hi:[0,1]
	v_mul_f32_e32 v52, v78, v78
	v_mul_f32_e32 v80, v79, v79
	v_mul_f32_e32 v50, v76, v76
	v_mul_f32_e32 v48, v77, v77
	v_pk_add_f32 v[52:53], v[52:53], v[80:81]
	v_pk_add_f32 v[48:49], v[50:51], v[48:49]
	s_nop 0
	v_pk_add_f32 v[48:49], v[52:53], v[48:49]
	s_nop 0
	v_add_f32_e32 v49, v48, v49
	ds_swizzle_b32 v50, v49 offset:swizzle(SWAP,16)
	v_add_u32_e32 v48, s23, v149
	s_waitcnt lgkmcnt(0)
;     __device__ __forceinline__ void operator()(const Acc& acc, const Unit& u, int wr, int wc, int fr, int fq) const {
;     ...
;             if (pn < 4) {
;                 const float* g = (pn < 2) ? qg : kg; bf16_t* dst = (pn < 2) ? Q : Kb;
;                 const float post = (pn < 2) ? 0.125f * LOG2E : 1.0f;
;                 const int head = 4 * (pn & 1) + wc;
; #pragma unroll
;                 for (int ai = 0; ai < 2; ++ai)
; #pragma unroll
;                     for (int m = 0; m < 4; ++m) {
;                         const int row = u.pm * 256 + ai * 128 + wr * 64 + m * 16 + fr;
;                         const float rs = rsv[ai][m];
;                         f32x4 v[2][2]; float ss = 0.f;
; #pragma unroll
;                         for (int bj = 0; bj < 2; ++bj)
; #pragma unroll
;                             for (int n = 0; n < 2; ++n) { v[bj][n] = acc[ai][bj][m][n] * rs; const f32x4 x = v[bj][n]; ss += (x[0] * x[0] + x[1] * x[1]) + (x[2] * x[2] + x[3] * x[3]); }
;                         ss += xshfl<16>(ss); ss += xshfl<32>(ss);
;                         const float hn = __builtin_amdgcn_rsqf(ss * (1.f / 64.f) + EPS) * post;
; #pragma unroll
;                         for (int bj = 0; bj < 2; ++bj) {
;                             float o[8];
; #pragma unroll
;                             for (int n = 0; n < 2; ++n) { const f32x4 gv = *(const f32x4*)(g + 32 * bj + 8 * fq + 4 * n);
; #pragma unroll
;                                 for (int j = 0; j < 4; ++j) o[4 * n + j] = v[bj][n][j] * hn * gv[j]; }
;                             st16(dst + (size_t)row * 512 + head * 64 + 32 * bj + 8 * fq, o);
;                         }
;                         asm volatile("" ::: "memory");
;                     }
	v_add_f32_e32 v49, v49, v50
	v_mov_b32_e32 v50, v49
	v_mov_b32_e32 v51, v49
	s_nop 1
	v_permlane32_swap_b32_e32 v50, v51
	v_cndmask_b32_e32 v50, v50, v51, vcc
	v_add_f32_e32 v49, v49, v50
	v_fmamk_f32 v49, v49, 0x3c800000, v212
	v_rsq_f32_e32 v50, v49
	v_ashrrev_i32_e32 v49, 31, v48
	v_lshlrev_b64 v[48:49], 10, v[48:49]
	v_lshl_add_u64 v[80:81], v[112:113], 0, v[48:49]
	v_mul_f32_e32 v82, v173, v50
	v_pk_mul_f32 v[48:49], v[60:61], v[82:83] op_sel_hi:[1,0]
	v_pk_mul_f32 v[50:51], v[62:63], v[82:83] op_sel_hi:[1,0]
	v_pk_mul_f32 v[52:53], v[56:57], v[82:83] op_sel_hi:[1,0]
	v_pk_mul_f32 v[54:55], v[58:59], v[82:83] op_sel_hi:[1,0]
	v_pk_mul_f32 v[56:57], v[74:75], v[82:83] op_sel_hi:[1,0]
	v_pk_mul_f32 v[58:59], v[72:73], v[82:83] op_sel_hi:[1,0]
	v_pk_mul_f32 v[60:61], v[78:79], v[82:83] op_sel_hi:[1,0]
	v_pk_mul_f32 v[62:63], v[76:77], v[82:83] op_sel_hi:[1,0]
	s_waitcnt vmcnt(1)
	v_pk_mul_f32 v[48:49], v[64:65], v[48:49]
	v_pk_mul_f32 v[50:51], v[66:67], v[50:51]
	s_waitcnt vmcnt(0)
	v_pk_mul_f32 v[52:53], v[68:69], v[52:53]
	v_pk_mul_f32 v[54:55], v[70:71], v[54:55]
	v_cvt_pk_bf16_f32 v48, v48, v49
	v_cvt_pk_bf16_f32 v49, v50, v51
	v_cvt_pk_bf16_f32 v50, v52, v53
	v_cvt_pk_bf16_f32 v51, v54, v55
	global_store_dwordx4 v[80:81], v[48:51], off
	s_nop 1
	v_pk_mul_f32 v[48:49], v[216:217], v[56:57]
	v_pk_mul_f32 v[50:51], v[218:219], v[58:59]
	v_pk_mul_f32 v[52:53], v[220:221], v[60:61]
	v_pk_mul_f32 v[54:55], v[222:223], v[62:63]
	v_cvt_pk_bf16_f32 v48, v48, v49
	v_cvt_pk_bf16_f32 v49, v50, v51
	v_cvt_pk_bf16_f32 v50, v52, v53
	v_cvt_pk_bf16_f32 v51, v54, v55
	global_store_dwordx4 v[80:81], v[48:51], off offset:64
	global_load_dwordx4 v[48:51], v171, s[0:1]
	global_load_dwordx4 v[52:55], v171, s[0:1] offset:16
	v_pk_mul_f32 v[56:57], v[174:175], v[38:39] op_sel_hi:[0,1]
	v_pk_mul_f32 v[58:59], v[174:175], v[36:37] op_sel_hi:[0,1]
	v_pk_mul_f32 v[60:61], v[174:175], v[34:35] op_sel_hi:[0,1]
	v_pk_mul_f32 v[62:63], v[174:175], v[32:33] op_sel_hi:[0,1]
	v_pk_mul_f32 v[32:33], v[46:47], v[46:47]
	v_pk_mul_f32 v[34:35], v[44:45], v[44:45]
	v_pk_mul_f32 v[36:37], v[42:43], v[42:43]
	v_pk_mul_f32 v[38:39], v[40:41], v[40:41]
	v_pk_mov_b32 v[68:69], v[34:35], v[32:33] op_sel:[1,0]
	v_mov_b32_e32 v35, v33
	v_pk_mov_b32 v[32:33], v[38:39], v[36:37] op_sel:[1,0]
	v_mov_b32_e32 v39, v37
	v_mul_f32_e32 v64, v58, v58
	v_mul_f32_e32 v66, v56, v56
	v_pk_add_f32 v[34:35], v[68:69], v[34:35]
	v_pk_add_f32 v[32:33], v[32:33], v[38:39]
	v_pk_fma_f32 v[36:37], v[58:59], v[58:59], v[64:65] op_sel_hi:[1,1,0]
	v_pk_fma_f32 v[64:65], v[56:57], v[56:57], v[66:67] op_sel_hi:[1,1,0]
	v_pk_add_f32 v[34:35], v[34:35], v[34:35] op_sel_hi:[0,1]
	v_pk_add_f32 v[32:33], v[32:33], v[32:33] op_sel_hi:[0,1]
	v_mul_f32_e32 v36, v62, v62
	v_mul_f32_e32 v64, v63, v63
	v_mul_f32_e32 v34, v60, v60
	v_mul_f32_e32 v32, v61, v61
	v_pk_add_f32 v[36:37], v[36:37], v[64:65]
	v_pk_add_f32 v[32:33], v[34:35], v[32:33]
	s_nop 0
	v_pk_add_f32 v[32:33], v[36:37], v[32:33]
	s_nop 0
	v_add_f32_e32 v33, v32, v33
	ds_swizzle_b32 v34, v33 offset:swizzle(SWAP,16)
	v_add_u32_e32 v32, s23, v151
	s_waitcnt lgkmcnt(0)
	v_add_f32_e32 v33, v33, v34
	v_mov_b32_e32 v34, v33
	v_mov_b32_e32 v35, v33
	s_nop 1
	v_permlane32_swap_b32_e32 v34, v35
	v_cndmask_b32_e32 v34, v34, v35, vcc
	v_add_f32_e32 v33, v33, v34
	v_fmamk_f32 v33, v33, 0x3c800000, v212
	v_rsq_f32_e32 v34, v33
	v_ashrrev_i32_e32 v33, 31, v32
	v_lshlrev_b64 v[32:33], 10, v[32:33]
	v_lshl_add_u64 v[64:65], v[112:113], 0, v[32:33]
	v_mul_f32_e32 v66, v173, v34
	v_pk_mul_f32 v[32:33], v[44:45], v[66:67] op_sel_hi:[1,0]
	v_pk_mul_f32 v[34:35], v[46:47], v[66:67] op_sel_hi:[1,0]
	v_pk_mul_f32 v[36:37], v[40:41], v[66:67] op_sel_hi:[1,0]
	v_pk_mul_f32 v[38:39], v[42:43], v[66:67] op_sel_hi:[1,0]
	v_pk_mul_f32 v[40:41], v[58:59], v[66:67] op_sel_hi:[1,0]
	v_pk_mul_f32 v[42:43], v[56:57], v[66:67] op_sel_hi:[1,0]
	v_pk_mul_f32 v[44:45], v[62:63], v[66:67] op_sel_hi:[1,0]
	v_pk_mul_f32 v[46:47], v[60:61], v[66:67] op_sel_hi:[1,0]
	s_waitcnt vmcnt(1)
	v_pk_mul_f32 v[32:33], v[48:49], v[32:33]
	v_pk_mul_f32 v[34:35], v[50:51], v[34:35]
	s_waitcnt vmcnt(0)
	v_pk_mul_f32 v[36:37], v[52:53], v[36:37]
	v_pk_mul_f32 v[38:39], v[54:55], v[38:39]
	v_cvt_pk_bf16_f32 v32, v32, v33
	v_cvt_pk_bf16_f32 v33, v34, v35
	v_cvt_pk_bf16_f32 v34, v36, v37
	v_cvt_pk_bf16_f32 v35, v38, v39
	global_store_dwordx4 v[64:65], v[32:35], off
	s_nop 1
	v_pk_mul_f32 v[32:33], v[216:217], v[40:41]
	v_pk_mul_f32 v[34:35], v[218:219], v[42:43]
	v_pk_mul_f32 v[36:37], v[220:221], v[44:45]
	v_pk_mul_f32 v[38:39], v[222:223], v[46:47]
	v_cvt_pk_bf16_f32 v32, v32, v33
	v_cvt_pk_bf16_f32 v33, v34, v35
	v_cvt_pk_bf16_f32 v34, v36, v37
	v_cvt_pk_bf16_f32 v35, v38, v39
	global_store_dwordx4 v[64:65], v[32:35], off offset:64
	global_load_dwordx4 v[32:35], v171, s[0:1]
	global_load_dwordx4 v[36:39], v171, s[0:1] offset:16
	v_pk_mul_f32 v[40:41], v[172:173], v[22:23] op_sel_hi:[0,1]
	v_pk_mul_f32 v[42:43], v[172:173], v[20:21] op_sel_hi:[0,1]
	v_pk_mul_f32 v[44:45], v[172:173], v[18:19] op_sel_hi:[0,1]
	v_pk_mul_f32 v[46:47], v[172:173], v[16:17] op_sel_hi:[0,1]
	v_pk_mul_f32 v[16:17], v[30:31], v[30:31]
	v_pk_mul_f32 v[18:19], v[28:29], v[28:29]
	v_pk_mul_f32 v[20:21], v[26:27], v[26:27]
	v_pk_mul_f32 v[22:23], v[24:25], v[24:25]
	v_pk_mov_b32 v[52:53], v[18:19], v[16:17] op_sel:[1,0]
	v_mov_b32_e32 v19, v17
	v_pk_mov_b32 v[16:17], v[22:23], v[20:21] op_sel:[1,0]
	v_mov_b32_e32 v23, v21
	v_mul_f32_e32 v48, v42, v42
	v_mul_f32_e32 v50, v40, v40
	v_pk_add_f32 v[18:19], v[52:53], v[18:19]
	v_pk_add_f32 v[16:17], v[16:17], v[22:23]
	v_pk_fma_f32 v[20:21], v[42:43], v[42:43], v[48:49] op_sel_hi:[1,1,0]
	v_pk_fma_f32 v[48:49], v[40:41], v[40:41], v[50:51] op_sel_hi:[1,1,0]
	v_pk_add_f32 v[18:19], v[18:19], v[18:19] op_sel_hi:[0,1]
	v_pk_add_f32 v[16:17], v[16:17], v[16:17] op_sel_hi:[0,1]
	v_mul_f32_e32 v20, v46, v46
	v_mul_f32_e32 v48, v47, v47
	v_mul_f32_e32 v18, v44, v44
	v_mul_f32_e32 v16, v45, v45
	v_pk_add_f32 v[20:21], v[20:21], v[48:49]
	v_pk_add_f32 v[16:17], v[18:19], v[16:17]
	s_nop 0
	v_pk_add_f32 v[16:17], v[20:21], v[16:17]
	s_nop 0
	v_add_f32_e32 v17, v16, v17
	ds_swizzle_b32 v18, v17 offset:swizzle(SWAP,16)
	v_add_u32_e32 v16, s23, v153
	s_waitcnt lgkmcnt(0)
;     __device__ __forceinline__ void operator()(const Acc& acc, const Unit& u, int wr, int wc, int fr, int fq) const {
;     ...
;             if (pn < 4) {
;                 const float* g = (pn < 2) ? qg : kg; bf16_t* dst = (pn < 2) ? Q : Kb;
;                 const float post = (pn < 2) ? 0.125f * LOG2E : 1.0f;
;                 const int head = 4 * (pn & 1) + wc;
; #pragma unroll
;                 for (int ai = 0; ai < 2; ++ai)
; #pragma unroll
;                     for (int m = 0; m < 4; ++m) {
;                         const int row = u.pm * 256 + ai * 128 + wr * 64 + m * 16 + fr;
;                         const float rs = rsv[ai][m];
;                         f32x4 v[2][2]; float ss = 0.f;
; #pragma unroll
;                         for (int bj = 0; bj < 2; ++bj)
; #pragma unroll
;                             for (int n = 0; n < 2; ++n) { v[bj][n] = acc[ai][bj][m][n] * rs; const f32x4 x = v[bj][n]; ss += (x[0] * x[0] + x[1] * x[1]) + (x[2] * x[2] + x[3] * x[3]); }
;                         ss += xshfl<16>(ss); ss += xshfl<32>(ss);
;                         const float hn = __builtin_amdgcn_rsqf(ss * (1.f / 64.f) + EPS) * post;
; #pragma unroll
;                         for (int bj = 0; bj < 2; ++bj) {
;                             float o[8];
; #pragma unroll
;                             for (int n = 0; n < 2; ++n) { const f32x4 gv = *(const f32x4*)(g + 32 * bj + 8 * fq + 4 * n);
; #pragma unroll
;                                 for (int j = 0; j < 4; ++j) o[4 * n + j] = v[bj][n][j] * hn * gv[j]; }
;                             st16(dst + (size_t)row * 512 + head * 64 + 32 * bj + 8 * fq, o);
;                         }
;                         asm volatile("" ::: "memory");
;                     }
	v_add_f32_e32 v17, v17, v18
	v_mov_b32_e32 v18, v17
	v_mov_b32_e32 v19, v17
	s_nop 1
	v_permlane32_swap_b32_e32 v18, v19
	v_cndmask_b32_e32 v18, v18, v19, vcc
	v_add_f32_e32 v17, v17, v18
	v_fmamk_f32 v17, v17, 0x3c800000, v212
	v_rsq_f32_e32 v18, v17
	v_ashrrev_i32_e32 v17, 31, v16
	v_lshlrev_b64 v[16:17], 10, v[16:17]
	v_lshl_add_u64 v[48:49], v[112:113], 0, v[16:17]
	v_mul_f32_e32 v50, v173, v18
	v_pk_mul_f32 v[16:17], v[28:29], v[50:51] op_sel_hi:[1,0]
	v_pk_mul_f32 v[18:19], v[30:31], v[50:51] op_sel_hi:[1,0]
	v_pk_mul_f32 v[20:21], v[24:25], v[50:51] op_sel_hi:[1,0]
	v_pk_mul_f32 v[22:23], v[26:27], v[50:51] op_sel_hi:[1,0]
	v_pk_mul_f32 v[24:25], v[42:43], v[50:51] op_sel_hi:[1,0]
	v_pk_mul_f32 v[26:27], v[40:41], v[50:51] op_sel_hi:[1,0]
	v_pk_mul_f32 v[28:29], v[46:47], v[50:51] op_sel_hi:[1,0]
	v_pk_mul_f32 v[30:31], v[44:45], v[50:51] op_sel_hi:[1,0]
	s_waitcnt vmcnt(1)
	v_pk_mul_f32 v[16:17], v[32:33], v[16:17]
	v_pk_mul_f32 v[18:19], v[34:35], v[18:19]
	s_waitcnt vmcnt(0)
	v_pk_mul_f32 v[20:21], v[36:37], v[20:21]
	v_pk_mul_f32 v[22:23], v[38:39], v[22:23]
	v_cvt_pk_bf16_f32 v16, v16, v17
	v_cvt_pk_bf16_f32 v17, v18, v19
	v_cvt_pk_bf16_f32 v18, v20, v21
	v_cvt_pk_bf16_f32 v19, v22, v23
	global_store_dwordx4 v[48:49], v[16:19], off
	s_nop 1
	v_pk_mul_f32 v[16:17], v[216:217], v[24:25]
	v_pk_mul_f32 v[18:19], v[218:219], v[26:27]
	v_pk_mul_f32 v[20:21], v[220:221], v[28:29]
	v_pk_mul_f32 v[22:23], v[222:223], v[30:31]
	v_cvt_pk_bf16_f32 v16, v16, v17
	v_cvt_pk_bf16_f32 v17, v18, v19
	v_cvt_pk_bf16_f32 v18, v20, v21
	v_cvt_pk_bf16_f32 v19, v22, v23
	global_store_dwordx4 v[48:49], v[16:19], off offset:64
	global_load_dwordx4 v[16:19], v171, s[0:1]
	global_load_dwordx4 v[20:23], v171, s[0:1] offset:16
	v_pk_mul_f32 v[24:25], v[170:171], v[6:7] op_sel_hi:[0,1]
	v_pk_mul_f32 v[26:27], v[170:171], v[4:5] op_sel_hi:[0,1]
	v_pk_mul_f32 v[28:29], v[170:171], v[2:3] op_sel_hi:[0,1]
	v_pk_mul_f32 v[30:31], v[170:171], v[0:1] op_sel_hi:[0,1]
	v_pk_mul_f32 v[0:1], v[14:15], v[14:15]
	v_pk_mul_f32 v[2:3], v[12:13], v[12:13]
	v_pk_mul_f32 v[4:5], v[10:11], v[10:11]
	v_pk_mul_f32 v[6:7], v[8:9], v[8:9]
	v_pk_mov_b32 v[36:37], v[2:3], v[0:1] op_sel:[1,0]
	v_mov_b32_e32 v3, v1
	v_pk_mov_b32 v[0:1], v[6:7], v[4:5] op_sel:[1,0]
	v_mov_b32_e32 v7, v5
	v_mul_f32_e32 v32, v26, v26
	v_mul_f32_e32 v34, v24, v24
	v_pk_add_f32 v[2:3], v[36:37], v[2:3]
	v_pk_add_f32 v[0:1], v[0:1], v[6:7]
	v_pk_fma_f32 v[4:5], v[26:27], v[26:27], v[32:33] op_sel_hi:[1,1,0]
	v_pk_fma_f32 v[32:33], v[24:25], v[24:25], v[34:35] op_sel_hi:[1,1,0]
	v_pk_add_f32 v[2:3], v[2:3], v[2:3] op_sel_hi:[0,1]
	v_pk_add_f32 v[0:1], v[0:1], v[0:1] op_sel_hi:[0,1]
	v_mul_f32_e32 v4, v30, v30
	v_mul_f32_e32 v32, v31, v31
	v_mul_f32_e32 v2, v28, v28
	v_mul_f32_e32 v0, v29, v29
	v_pk_add_f32 v[4:5], v[4:5], v[32:33]
	v_pk_add_f32 v[0:1], v[2:3], v[0:1]
	s_nop 0
	v_pk_add_f32 v[0:1], v[4:5], v[0:1]
	s_nop 0
	v_add_f32_e32 v1, v0, v1
	ds_swizzle_b32 v2, v1 offset:swizzle(SWAP,16)
	v_add_u32_e32 v0, s23, v155
	s_waitcnt lgkmcnt(0)
	v_add_f32_e32 v1, v1, v2
	v_mov_b32_e32 v2, v1
	v_mov_b32_e32 v3, v1
	s_nop 1
	v_permlane32_swap_b32_e32 v2, v3
	v_cndmask_b32_e32 v2, v2, v3, vcc
	v_add_f32_e32 v1, v1, v2
	v_fmamk_f32 v1, v1, 0x3c800000, v212
	v_rsq_f32_e32 v2, v1
	v_ashrrev_i32_e32 v1, 31, v0
	v_lshlrev_b64 v[0:1], 10, v[0:1]
	v_lshl_add_u64 v[32:33], v[112:113], 0, v[0:1]
	v_mul_f32_e32 v34, v173, v2
	v_pk_mul_f32 v[0:1], v[12:13], v[34:35] op_sel_hi:[1,0]
	v_pk_mul_f32 v[2:3], v[14:15], v[34:35] op_sel_hi:[1,0]
	v_pk_mul_f32 v[4:5], v[8:9], v[34:35] op_sel_hi:[1,0]
	v_pk_mul_f32 v[6:7], v[10:11], v[34:35] op_sel_hi:[1,0]
	v_pk_mul_f32 v[8:9], v[26:27], v[34:35] op_sel_hi:[1,0]
	v_pk_mul_f32 v[10:11], v[24:25], v[34:35] op_sel_hi:[1,0]
	v_pk_mul_f32 v[12:13], v[30:31], v[34:35] op_sel_hi:[1,0]
	v_pk_mul_f32 v[14:15], v[28:29], v[34:35] op_sel_hi:[1,0]
	s_waitcnt vmcnt(1)
	v_pk_mul_f32 v[0:1], v[16:17], v[0:1]
	v_pk_mul_f32 v[2:3], v[18:19], v[2:3]
	s_waitcnt vmcnt(0)
	v_pk_mul_f32 v[4:5], v[20:21], v[4:5]
	v_pk_mul_f32 v[6:7], v[22:23], v[6:7]
	v_cvt_pk_bf16_f32 v0, v0, v1
	v_cvt_pk_bf16_f32 v1, v2, v3
	v_cvt_pk_bf16_f32 v2, v4, v5
	v_cvt_pk_bf16_f32 v3, v6, v7
	global_store_dwordx4 v[32:33], v[0:3], off
	s_nop 1
	v_pk_mul_f32 v[0:1], v[216:217], v[8:9]
	v_pk_mul_f32 v[2:3], v[218:219], v[10:11]
	v_pk_mul_f32 v[4:5], v[220:221], v[12:13]
	v_pk_mul_f32 v[6:7], v[222:223], v[14:15]
	v_cvt_pk_bf16_f32 v0, v0, v1
	v_cvt_pk_bf16_f32 v1, v2, v3
	v_cvt_pk_bf16_f32 v2, v4, v5
	v_cvt_pk_bf16_f32 v3, v6, v7
	global_store_dwordx4 v[32:33], v[0:3], off offset:64
